# wave-1 L1 invalidate delayed ~1.5us after the entry barrier so it does not queue in front of lane 0's arrival atomic
# baseline (speedup 1.0000x reference)
; __device__ __forceinline__ void xcd_barrier(const XcdBarrier& b) {
;     asm volatile("s_waitcnt vmcnt(0)" ::: "memory");
;     __syncthreads();
;     ...
;             __builtin_amdgcn_fence(__ATOMIC_ACQUIRE, "agent");
;             asm volatile("s_waitcnt vmcnt(0)" ::: "memory");
.LBB0_59:
	s_waitcnt vmcnt(0)
	s_waitcnt lgkmcnt(0)
	s_barrier
	v_readfirstlane_b32 s0, v212
	s_cmp_lg_u32 s0, 64
	s_cbranch_scc1 .Linv_0
	s_sleep 48
	buffer_inv sc1
	s_waitcnt vmcnt(0)

; __device__ __forceinline__ void xcd_barrier(const XcdBarrier& b) {
;     asm volatile("s_waitcnt vmcnt(0)" ::: "memory");
;     __syncthreads();
;     ...
;             __builtin_amdgcn_fence(__ATOMIC_ACQUIRE, "agent");
;             asm volatile("s_waitcnt vmcnt(0)" ::: "memory");
.LBB0_342:
	s_waitcnt vmcnt(0)
	s_barrier
	s_waitcnt vmcnt(0)
	s_waitcnt vmcnt(0)
	s_barrier
	v_readfirstlane_b32 s0, v212
	s_cmp_lg_u32 s0, 64
	s_cbranch_scc1 .Linv_1
	s_sleep 48
	buffer_inv sc1
	s_waitcnt vmcnt(0)

; __device__ __forceinline__ void xcd_barrier(const XcdBarrier& b) {
;     asm volatile("s_waitcnt vmcnt(0)" ::: "memory");
;     __syncthreads();
;     ...
;             __builtin_amdgcn_fence(__ATOMIC_ACQUIRE, "agent");
;             asm volatile("s_waitcnt vmcnt(0)" ::: "memory");
.LBB0_465:
	s_or_b64 exec, exec, s[6:7]
	s_waitcnt vmcnt(0)
	s_barrier
	v_readfirstlane_b32 s0, v212
	s_cmp_lg_u32 s0, 64
	s_cbranch_scc1 .Linv_2
	s_sleep 48
	buffer_inv sc1
	s_waitcnt vmcnt(0)

; __device__ __forceinline__ void xcd_barrier(const XcdBarrier& b) {
;     asm volatile("s_waitcnt vmcnt(0)" ::: "memory");
;     __syncthreads();
;     ...
;             __builtin_amdgcn_fence(__ATOMIC_ACQUIRE, "agent");
;             asm volatile("s_waitcnt vmcnt(0)" ::: "memory");
.LBB0_560:
	s_waitcnt vmcnt(0)
	s_barrier
	v_readfirstlane_b32 s0, v212
	s_cmp_lg_u32 s0, 64
	s_cbranch_scc1 .Linv_3
	s_sleep 48
	buffer_inv sc1
	s_waitcnt vmcnt(0)

; __device__ __forceinline__ unsigned cvt_pk_bf16(float lo, float hi) { unsigned r; asm volatile("v_cvt_pk_bf16_f32 %0, %1, %2" : "=v"(r) : "v"(lo), "v"(hi)); return r; }
; __device__ __forceinline__ float bf_lo(unsigned w) { return __uint_as_float(w << 16); }
; __device__ __forceinline__ float bf_hi(unsigned w) { return __uint_as_float(w & 0xffff0000u); }
; __global__ void __launch_bounds__(NTHR, 2) hybrid_block_fwd(Args a) {
;     ...
;         for (int i = 0; i < CH_L; ++i) {
;             const u32x2 q = pab[(size_t)i * (LW / 2)]; const f32x2 av = (f32x2){__builtin_amdgcn_exp2f(bf_lo(q.x)), __builtin_amdgcn_exp2f(bf_lo(q.y))}, bv = (f32x2){bf_hi(q.x), bf_hi(q.y)}; const unsigned gq = pg[(size_t)i * (LW / 2)];
;             H = av * H + bv;
;             po[(size_t)i * (KC / 2)] = cvt_pk_bf16(H.x * bf_lo(gq), H.y * bf_hi(gq));
;         }
.Lp2d_steady:
	s_waitcnt vmcnt(45)
	v_lshlrev_b32_e32 v8, 16, v32
	v_lshlrev_b32_e32 v9, 16, v33
	v_exp_f32_e32 v8, v8
	v_exp_f32_e32 v9, v9
	v_and_b32_e32 v10, 0xffff0000, v32
	v_and_b32_e32 v11, 0xffff0000, v33
	v_lshlrev_b32_e32 v12, 16, v64
	v_and_b32_e32 v13, 0xffff0000, v64
	v_pk_fma_f32 v[4:5], v[4:5], v[8:9], v[10:11]
	v_mul_f32_e32 v12, v4, v12
	v_mul_f32_e32 v13, v5, v13
	v_cvt_pk_bf16_f32 v12, v12, v13
	global_store_dword v3, v12, s[18:19]
	s_add_u32 s18, s18, 0x1800
	s_addc_u32 s19, s19, 0
	global_load_dwordx2 v[32:33], v2, s[12:13] nt
	global_load_dword v64, v3, s[14:15] nt
	s_add_u32 s12, s12, 0x2000
	s_addc_u32 s13, s13, 0
	s_add_u32 s14, s14, 0x1000
	s_addc_u32 s15, s15, 0
	s_waitcnt vmcnt(45)
	v_lshlrev_b32_e32 v16, 16, v34
	v_lshlrev_b32_e32 v17, 16, v35
	v_exp_f32_e32 v16, v16
	v_exp_f32_e32 v17, v17
	v_and_b32_e32 v18, 0xffff0000, v34
	v_and_b32_e32 v19, 0xffff0000, v35
	v_lshlrev_b32_e32 v20, 16, v65
	v_and_b32_e32 v21, 0xffff0000, v65
	v_pk_fma_f32 v[4:5], v[4:5], v[16:17], v[18:19]
	v_mul_f32_e32 v20, v4, v20
	v_mul_f32_e32 v21, v5, v21
	v_cvt_pk_bf16_f32 v20, v20, v21
	global_store_dword v3, v20, s[18:19]
	s_add_u32 s18, s18, 0x1800
	s_addc_u32 s19, s19, 0
	global_load_dwordx2 v[34:35], v2, s[12:13] nt
	global_load_dword v65, v3, s[14:15] nt
	s_add_u32 s12, s12, 0x2000
	s_addc_u32 s13, s13, 0
	s_add_u32 s14, s14, 0x1000
	s_addc_u32 s15, s15, 0
	s_waitcnt vmcnt(45)
	v_lshlrev_b32_e32 v8, 16, v36
	v_lshlrev_b32_e32 v9, 16, v37
	v_exp_f32_e32 v8, v8
	v_exp_f32_e32 v9, v9
	v_and_b32_e32 v10, 0xffff0000, v36
	v_and_b32_e32 v11, 0xffff0000, v37
	v_lshlrev_b32_e32 v12, 16, v66
	v_and_b32_e32 v13, 0xffff0000, v66
	v_pk_fma_f32 v[4:5], v[4:5], v[8:9], v[10:11]
	v_mul_f32_e32 v12, v4, v12
	v_mul_f32_e32 v13, v5, v13
	v_cvt_pk_bf16_f32 v12, v12, v13
	global_store_dword v3, v12, s[18:19]
	s_add_u32 s18, s18, 0x1800
	s_addc_u32 s19, s19, 0
	global_load_dwordx2 v[36:37], v2, s[12:13] nt
	global_load_dword v66, v3, s[14:15] nt
	s_add_u32 s12, s12, 0x2000
	s_addc_u32 s13, s13, 0
	s_add_u32 s14, s14, 0x1000
	s_addc_u32 s15, s15, 0
	s_waitcnt vmcnt(45)
	v_lshlrev_b32_e32 v16, 16, v38
	v_lshlrev_b32_e32 v17, 16, v39
	v_exp_f32_e32 v16, v16
	v_exp_f32_e32 v17, v17
	v_and_b32_e32 v18, 0xffff0000, v38
	v_and_b32_e32 v19, 0xffff0000, v39
	v_lshlrev_b32_e32 v20, 16, v67
	v_and_b32_e32 v21, 0xffff0000, v67
	v_pk_fma_f32 v[4:5], v[4:5], v[16:17], v[18:19]
	v_mul_f32_e32 v20, v4, v20
	v_mul_f32_e32 v21, v5, v21
	v_cvt_pk_bf16_f32 v20, v20, v21
	global_store_dword v3, v20, s[18:19]
	s_add_u32 s18, s18, 0x1800
	s_addc_u32 s19, s19, 0
	global_load_dwordx2 v[38:39], v2, s[12:13] nt
	global_load_dword v67, v3, s[14:15] nt
	s_add_u32 s12, s12, 0x2000
	s_addc_u32 s13, s13, 0
	s_add_u32 s14, s14, 0x1000
	s_addc_u32 s15, s15, 0
	s_waitcnt vmcnt(45)
	v_lshlrev_b32_e32 v8, 16, v40
	v_lshlrev_b32_e32 v9, 16, v41
	v_exp_f32_e32 v8, v8
	v_exp_f32_e32 v9, v9
	v_and_b32_e32 v10, 0xffff0000, v40
	v_and_b32_e32 v11, 0xffff0000, v41
	v_lshlrev_b32_e32 v12, 16, v68
	v_and_b32_e32 v13, 0xffff0000, v68
	v_pk_fma_f32 v[4:5], v[4:5], v[8:9], v[10:11]
	v_mul_f32_e32 v12, v4, v12
	v_mul_f32_e32 v13, v5, v13
	v_cvt_pk_bf16_f32 v12, v12, v13
	global_store_dword v3, v12, s[18:19]
	s_add_u32 s18, s18, 0x1800
	s_addc_u32 s19, s19, 0
	global_load_dwordx2 v[40:41], v2, s[12:13] nt
	global_load_dword v68, v3, s[14:15] nt
	s_add_u32 s12, s12, 0x2000
	s_addc_u32 s13, s13, 0
	s_add_u32 s14, s14, 0x1000
	s_addc_u32 s15, s15, 0
	s_waitcnt vmcnt(45)
	v_lshlrev_b32_e32 v16, 16, v42
	v_lshlrev_b32_e32 v17, 16, v43
	v_exp_f32_e32 v16, v16
	v_exp_f32_e32 v17, v17
	v_and_b32_e32 v18, 0xffff0000, v42
	v_and_b32_e32 v19, 0xffff0000, v43
	v_lshlrev_b32_e32 v20, 16, v69
	v_and_b32_e32 v21, 0xffff0000, v69
	v_pk_fma_f32 v[4:5], v[4:5], v[16:17], v[18:19]
	v_mul_f32_e32 v20, v4, v20
	v_mul_f32_e32 v21, v5, v21
	v_cvt_pk_bf16_f32 v20, v20, v21
	global_store_dword v3, v20, s[18:19]
	s_add_u32 s18, s18, 0x1800
	s_addc_u32 s19, s19, 0
	global_load_dwordx2 v[42:43], v2, s[12:13] nt
	global_load_dword v69, v3, s[14:15] nt
	s_add_u32 s12, s12, 0x2000
	s_addc_u32 s13, s13, 0
	s_add_u32 s14, s14, 0x1000
	s_addc_u32 s15, s15, 0
	s_waitcnt vmcnt(45)
	v_lshlrev_b32_e32 v8, 16, v44
	v_lshlrev_b32_e32 v9, 16, v45
	v_exp_f32_e32 v8, v8
	v_exp_f32_e32 v9, v9
	v_and_b32_e32 v10, 0xffff0000, v44
	v_and_b32_e32 v11, 0xffff0000, v45
	v_lshlrev_b32_e32 v12, 16, v70
	v_and_b32_e32 v13, 0xffff0000, v70
	v_pk_fma_f32 v[4:5], v[4:5], v[8:9], v[10:11]
	v_mul_f32_e32 v12, v4, v12
	v_mul_f32_e32 v13, v5, v13
	v_cvt_pk_bf16_f32 v12, v12, v13
	global_store_dword v3, v12, s[18:19]
	s_add_u32 s18, s18, 0x1800
	s_addc_u32 s19, s19, 0
	global_load_dwordx2 v[44:45], v2, s[12:13] nt
	global_load_dword v70, v3, s[14:15] nt
	s_add_u32 s12, s12, 0x2000
	s_addc_u32 s13, s13, 0
	s_add_u32 s14, s14, 0x1000
	s_addc_u32 s15, s15, 0
	s_waitcnt vmcnt(45)
	v_lshlrev_b32_e32 v16, 16, v46
	v_lshlrev_b32_e32 v17, 16, v47
	v_exp_f32_e32 v16, v16
	v_exp_f32_e32 v17, v17
	v_and_b32_e32 v18, 0xffff0000, v46
	v_and_b32_e32 v19, 0xffff0000, v47
	v_lshlrev_b32_e32 v20, 16, v71
	v_and_b32_e32 v21, 0xffff0000, v71
	v_pk_fma_f32 v[4:5], v[4:5], v[16:17], v[18:19]
	v_mul_f32_e32 v20, v4, v20
	v_mul_f32_e32 v21, v5, v21
	v_cvt_pk_bf16_f32 v20, v20, v21
	global_store_dword v3, v20, s[18:19]
	s_add_u32 s18, s18, 0x1800
	s_addc_u32 s19, s19, 0
	global_load_dwordx2 v[46:47], v2, s[12:13] nt
	global_load_dword v71, v3, s[14:15] nt
	s_add_u32 s12, s12, 0x2000
	s_addc_u32 s13, s13, 0
	s_add_u32 s14, s14, 0x1000
	s_addc_u32 s15, s15, 0
	s_waitcnt vmcnt(45)
; __device__ __forceinline__ unsigned cvt_pk_bf16(float lo, float hi) { unsigned r; asm volatile("v_cvt_pk_bf16_f32 %0, %1, %2" : "=v"(r) : "v"(lo), "v"(hi)); return r; }
; __device__ __forceinline__ float bf_lo(unsigned w) { return __uint_as_float(w << 16); }
; __device__ __forceinline__ float bf_hi(unsigned w) { return __uint_as_float(w & 0xffff0000u); }
; __global__ void __launch_bounds__(NTHR, 2) hybrid_block_fwd(Args a) {
;     ...
;         for (int i = 0; i < CH_L; ++i) {
;             const u32x2 q = pab[(size_t)i * (LW / 2)]; const f32x2 av = (f32x2){__builtin_amdgcn_exp2f(bf_lo(q.x)), __builtin_amdgcn_exp2f(bf_lo(q.y))}, bv = (f32x2){bf_hi(q.x), bf_hi(q.y)}; const unsigned gq = pg[(size_t)i * (LW / 2)];
;             H = av * H + bv;
;             po[(size_t)i * (KC / 2)] = cvt_pk_bf16(H.x * bf_lo(gq), H.y * bf_hi(gq));
;         }
	v_lshlrev_b32_e32 v8, 16, v48
	v_lshlrev_b32_e32 v9, 16, v49
	v_exp_f32_e32 v8, v8
	v_exp_f32_e32 v9, v9
	v_and_b32_e32 v10, 0xffff0000, v48
	v_and_b32_e32 v11, 0xffff0000, v49
	v_lshlrev_b32_e32 v12, 16, v72
	v_and_b32_e32 v13, 0xffff0000, v72
	v_pk_fma_f32 v[4:5], v[4:5], v[8:9], v[10:11]
	v_mul_f32_e32 v12, v4, v12
	v_mul_f32_e32 v13, v5, v13
	v_cvt_pk_bf16_f32 v12, v12, v13
	global_store_dword v3, v12, s[18:19]
	s_add_u32 s18, s18, 0x1800
	s_addc_u32 s19, s19, 0
	global_load_dwordx2 v[48:49], v2, s[12:13] nt
	global_load_dword v72, v3, s[14:15] nt
	s_add_u32 s12, s12, 0x2000
	s_addc_u32 s13, s13, 0
	s_add_u32 s14, s14, 0x1000
	s_addc_u32 s15, s15, 0
	s_waitcnt vmcnt(45)
	v_lshlrev_b32_e32 v16, 16, v50
	v_lshlrev_b32_e32 v17, 16, v51
	v_exp_f32_e32 v16, v16
	v_exp_f32_e32 v17, v17
	v_and_b32_e32 v18, 0xffff0000, v50
	v_and_b32_e32 v19, 0xffff0000, v51
	v_lshlrev_b32_e32 v20, 16, v73
	v_and_b32_e32 v21, 0xffff0000, v73
	v_pk_fma_f32 v[4:5], v[4:5], v[16:17], v[18:19]
	v_mul_f32_e32 v20, v4, v20
	v_mul_f32_e32 v21, v5, v21
	v_cvt_pk_bf16_f32 v20, v20, v21
	global_store_dword v3, v20, s[18:19]
	s_add_u32 s18, s18, 0x1800
	s_addc_u32 s19, s19, 0
	global_load_dwordx2 v[50:51], v2, s[12:13] nt
	global_load_dword v73, v3, s[14:15] nt
	s_add_u32 s12, s12, 0x2000
	s_addc_u32 s13, s13, 0
	s_add_u32 s14, s14, 0x1000
	s_addc_u32 s15, s15, 0
	s_waitcnt vmcnt(45)
	v_lshlrev_b32_e32 v8, 16, v52
	v_lshlrev_b32_e32 v9, 16, v53
	v_exp_f32_e32 v8, v8
	v_exp_f32_e32 v9, v9
	v_and_b32_e32 v10, 0xffff0000, v52
	v_and_b32_e32 v11, 0xffff0000, v53
	v_lshlrev_b32_e32 v12, 16, v74
	v_and_b32_e32 v13, 0xffff0000, v74
	v_pk_fma_f32 v[4:5], v[4:5], v[8:9], v[10:11]
	v_mul_f32_e32 v12, v4, v12
	v_mul_f32_e32 v13, v5, v13
	v_cvt_pk_bf16_f32 v12, v12, v13
	global_store_dword v3, v12, s[18:19]
	s_add_u32 s18, s18, 0x1800
	s_addc_u32 s19, s19, 0
	global_load_dwordx2 v[52:53], v2, s[12:13] nt
	global_load_dword v74, v3, s[14:15] nt
	s_add_u32 s12, s12, 0x2000
	s_addc_u32 s13, s13, 0
	s_add_u32 s14, s14, 0x1000
	s_addc_u32 s15, s15, 0
	s_waitcnt vmcnt(45)
	v_lshlrev_b32_e32 v16, 16, v54
	v_lshlrev_b32_e32 v17, 16, v55
	v_exp_f32_e32 v16, v16
	v_exp_f32_e32 v17, v17
	v_and_b32_e32 v18, 0xffff0000, v54
	v_and_b32_e32 v19, 0xffff0000, v55
	v_lshlrev_b32_e32 v20, 16, v75
	v_and_b32_e32 v21, 0xffff0000, v75
	v_pk_fma_f32 v[4:5], v[4:5], v[16:17], v[18:19]
	v_mul_f32_e32 v20, v4, v20
	v_mul_f32_e32 v21, v5, v21
	v_cvt_pk_bf16_f32 v20, v20, v21
	global_store_dword v3, v20, s[18:19]
	s_add_u32 s18, s18, 0x1800
	s_addc_u32 s19, s19, 0
	global_load_dwordx2 v[54:55], v2, s[12:13] nt
	global_load_dword v75, v3, s[14:15] nt
	s_add_u32 s12, s12, 0x2000
	s_addc_u32 s13, s13, 0
	s_add_u32 s14, s14, 0x1000
	s_addc_u32 s15, s15, 0
	s_waitcnt vmcnt(45)
	v_lshlrev_b32_e32 v8, 16, v56
	v_lshlrev_b32_e32 v9, 16, v57
	v_exp_f32_e32 v8, v8
	v_exp_f32_e32 v9, v9
	v_and_b32_e32 v10, 0xffff0000, v56
	v_and_b32_e32 v11, 0xffff0000, v57
	v_lshlrev_b32_e32 v12, 16, v76
	v_and_b32_e32 v13, 0xffff0000, v76
	v_pk_fma_f32 v[4:5], v[4:5], v[8:9], v[10:11]
	v_mul_f32_e32 v12, v4, v12
	v_mul_f32_e32 v13, v5, v13
	v_cvt_pk_bf16_f32 v12, v12, v13
	global_store_dword v3, v12, s[18:19]
	s_add_u32 s18, s18, 0x1800
	s_addc_u32 s19, s19, 0
	global_load_dwordx2 v[56:57], v2, s[12:13] nt
	global_load_dword v76, v3, s[14:15] nt
	s_add_u32 s12, s12, 0x2000
	s_addc_u32 s13, s13, 0
	s_add_u32 s14, s14, 0x1000
	s_addc_u32 s15, s15, 0
	s_waitcnt vmcnt(45)
	v_lshlrev_b32_e32 v16, 16, v58
	v_lshlrev_b32_e32 v17, 16, v59
	v_exp_f32_e32 v16, v16
	v_exp_f32_e32 v17, v17
	v_and_b32_e32 v18, 0xffff0000, v58
	v_and_b32_e32 v19, 0xffff0000, v59
	v_lshlrev_b32_e32 v20, 16, v77
	v_and_b32_e32 v21, 0xffff0000, v77
	v_pk_fma_f32 v[4:5], v[4:5], v[16:17], v[18:19]
	v_mul_f32_e32 v20, v4, v20
	v_mul_f32_e32 v21, v5, v21
	v_cvt_pk_bf16_f32 v20, v20, v21
	global_store_dword v3, v20, s[18:19]
	s_add_u32 s18, s18, 0x1800
	s_addc_u32 s19, s19, 0
	global_load_dwordx2 v[58:59], v2, s[12:13] nt
	global_load_dword v77, v3, s[14:15] nt
	s_add_u32 s12, s12, 0x2000
	s_addc_u32 s13, s13, 0
	s_add_u32 s14, s14, 0x1000
	s_addc_u32 s15, s15, 0
	s_waitcnt vmcnt(45)
	v_lshlrev_b32_e32 v8, 16, v60
	v_lshlrev_b32_e32 v9, 16, v61
	v_exp_f32_e32 v8, v8
	v_exp_f32_e32 v9, v9
	v_and_b32_e32 v10, 0xffff0000, v60
	v_and_b32_e32 v11, 0xffff0000, v61
	v_lshlrev_b32_e32 v12, 16, v78
	v_and_b32_e32 v13, 0xffff0000, v78
	v_pk_fma_f32 v[4:5], v[4:5], v[8:9], v[10:11]
	v_mul_f32_e32 v12, v4, v12
	v_mul_f32_e32 v13, v5, v13
	v_cvt_pk_bf16_f32 v12, v12, v13
	global_store_dword v3, v12, s[18:19]
	s_add_u32 s18, s18, 0x1800
	s_addc_u32 s19, s19, 0
	global_load_dwordx2 v[60:61], v2, s[12:13] nt
	global_load_dword v78, v3, s[14:15] nt
	s_add_u32 s12, s12, 0x2000
	s_addc_u32 s13, s13, 0
	s_add_u32 s14, s14, 0x1000
	s_addc_u32 s15, s15, 0
	s_waitcnt vmcnt(45)
	v_lshlrev_b32_e32 v16, 16, v62
	v_lshlrev_b32_e32 v17, 16, v63
	v_exp_f32_e32 v16, v16
	v_exp_f32_e32 v17, v17
	v_and_b32_e32 v18, 0xffff0000, v62
	v_and_b32_e32 v19, 0xffff0000, v63
	v_lshlrev_b32_e32 v20, 16, v79
	v_and_b32_e32 v21, 0xffff0000, v79
	v_pk_fma_f32 v[4:5], v[4:5], v[16:17], v[18:19]
	v_mul_f32_e32 v20, v4, v20
	v_mul_f32_e32 v21, v5, v21
	v_cvt_pk_bf16_f32 v20, v20, v21
	global_store_dword v3, v20, s[18:19]
	s_add_u32 s18, s18, 0x1800
	s_addc_u32 s19, s19, 0
	global_load_dwordx2 v[62:63], v2, s[12:13] nt
	global_load_dword v79, v3, s[14:15] nt
	s_add_u32 s12, s12, 0x2000
	s_addc_u32 s13, s13, 0
	s_add_u32 s14, s14, 0x1000
	s_addc_u32 s15, s15, 0
	s_sub_u32 s22, s22, 1
	s_cmp_lg_u32 s22, 0
	s_cbranch_scc1 .Lp2d_steady
; __device__ __forceinline__ unsigned cvt_pk_bf16(float lo, float hi) { unsigned r; asm volatile("v_cvt_pk_bf16_f32 %0, %1, %2" : "=v"(r) : "v"(lo), "v"(hi)); return r; }
; __device__ __forceinline__ float bf_lo(unsigned w) { return __uint_as_float(w << 16); }
; __device__ __forceinline__ float bf_hi(unsigned w) { return __uint_as_float(w & 0xffff0000u); }
; __global__ void __launch_bounds__(NTHR, 2) hybrid_block_fwd(Args a) {
;     ...
;         for (int i = 0; i < CH_L; ++i) {
;             const u32x2 q = pab[(size_t)i * (LW / 2)]; const f32x2 av = (f32x2){__builtin_amdgcn_exp2f(bf_lo(q.x)), __builtin_amdgcn_exp2f(bf_lo(q.y))}, bv = (f32x2){bf_hi(q.x), bf_hi(q.y)}; const unsigned gq = pg[(size_t)i * (LW / 2)];
;             H = av * H + bv;
;             po[(size_t)i * (KC / 2)] = cvt_pk_bf16(H.x * bf_lo(gq), H.y * bf_hi(gq));
;         }
	s_waitcnt vmcnt(45)
	v_lshlrev_b32_e32 v8, 16, v32
	v_lshlrev_b32_e32 v9, 16, v33
	v_exp_f32_e32 v8, v8
	v_exp_f32_e32 v9, v9
	v_and_b32_e32 v10, 0xffff0000, v32
	v_and_b32_e32 v11, 0xffff0000, v33
	v_lshlrev_b32_e32 v12, 16, v64
	v_and_b32_e32 v13, 0xffff0000, v64
	v_pk_fma_f32 v[4:5], v[4:5], v[8:9], v[10:11]
	v_mul_f32_e32 v12, v4, v12
	v_mul_f32_e32 v13, v5, v13
	v_cvt_pk_bf16_f32 v12, v12, v13
	global_store_dword v3, v12, s[18:19]
	s_add_u32 s18, s18, 0x1800
	s_addc_u32 s19, s19, 0
	s_waitcnt vmcnt(43)
	v_lshlrev_b32_e32 v16, 16, v34
	v_lshlrev_b32_e32 v17, 16, v35
	v_exp_f32_e32 v16, v16
	v_exp_f32_e32 v17, v17
	v_and_b32_e32 v18, 0xffff0000, v34
	v_and_b32_e32 v19, 0xffff0000, v35
	v_lshlrev_b32_e32 v20, 16, v65
	v_and_b32_e32 v21, 0xffff0000, v65
	v_pk_fma_f32 v[4:5], v[4:5], v[16:17], v[18:19]
	v_mul_f32_e32 v20, v4, v20
	v_mul_f32_e32 v21, v5, v21
	v_cvt_pk_bf16_f32 v20, v20, v21
	global_store_dword v3, v20, s[18:19]
	s_add_u32 s18, s18, 0x1800
	s_addc_u32 s19, s19, 0
	s_waitcnt vmcnt(41)
	v_lshlrev_b32_e32 v8, 16, v36
	v_lshlrev_b32_e32 v9, 16, v37
	v_exp_f32_e32 v8, v8
	v_exp_f32_e32 v9, v9
	v_and_b32_e32 v10, 0xffff0000, v36
	v_and_b32_e32 v11, 0xffff0000, v37
	v_lshlrev_b32_e32 v12, 16, v66
	v_and_b32_e32 v13, 0xffff0000, v66
	v_pk_fma_f32 v[4:5], v[4:5], v[8:9], v[10:11]
	v_mul_f32_e32 v12, v4, v12
	v_mul_f32_e32 v13, v5, v13
	v_cvt_pk_bf16_f32 v12, v12, v13
	global_store_dword v3, v12, s[18:19]
	s_add_u32 s18, s18, 0x1800
	s_addc_u32 s19, s19, 0
	s_waitcnt vmcnt(39)
	v_lshlrev_b32_e32 v16, 16, v38
	v_lshlrev_b32_e32 v17, 16, v39
	v_exp_f32_e32 v16, v16
	v_exp_f32_e32 v17, v17
	v_and_b32_e32 v18, 0xffff0000, v38
	v_and_b32_e32 v19, 0xffff0000, v39
	v_lshlrev_b32_e32 v20, 16, v67
	v_and_b32_e32 v21, 0xffff0000, v67
	v_pk_fma_f32 v[4:5], v[4:5], v[16:17], v[18:19]
	v_mul_f32_e32 v20, v4, v20
	v_mul_f32_e32 v21, v5, v21
	v_cvt_pk_bf16_f32 v20, v20, v21
	global_store_dword v3, v20, s[18:19]
	s_add_u32 s18, s18, 0x1800
	s_addc_u32 s19, s19, 0
	s_waitcnt vmcnt(37)
	v_lshlrev_b32_e32 v8, 16, v40
	v_lshlrev_b32_e32 v9, 16, v41
	v_exp_f32_e32 v8, v8
	v_exp_f32_e32 v9, v9
	v_and_b32_e32 v10, 0xffff0000, v40
	v_and_b32_e32 v11, 0xffff0000, v41
	v_lshlrev_b32_e32 v12, 16, v68
	v_and_b32_e32 v13, 0xffff0000, v68
	v_pk_fma_f32 v[4:5], v[4:5], v[8:9], v[10:11]
	v_mul_f32_e32 v12, v4, v12
	v_mul_f32_e32 v13, v5, v13
	v_cvt_pk_bf16_f32 v12, v12, v13
	global_store_dword v3, v12, s[18:19]
	s_add_u32 s18, s18, 0x1800
	s_addc_u32 s19, s19, 0
	s_waitcnt vmcnt(35)
	v_lshlrev_b32_e32 v16, 16, v42
	v_lshlrev_b32_e32 v17, 16, v43
	v_exp_f32_e32 v16, v16
	v_exp_f32_e32 v17, v17
	v_and_b32_e32 v18, 0xffff0000, v42
	v_and_b32_e32 v19, 0xffff0000, v43
	v_lshlrev_b32_e32 v20, 16, v69
	v_and_b32_e32 v21, 0xffff0000, v69
	v_pk_fma_f32 v[4:5], v[4:5], v[16:17], v[18:19]
	v_mul_f32_e32 v20, v4, v20
	v_mul_f32_e32 v21, v5, v21
	v_cvt_pk_bf16_f32 v20, v20, v21
	global_store_dword v3, v20, s[18:19]
	s_add_u32 s18, s18, 0x1800
	s_addc_u32 s19, s19, 0
	s_waitcnt vmcnt(33)
	v_lshlrev_b32_e32 v8, 16, v44
	v_lshlrev_b32_e32 v9, 16, v45
	v_exp_f32_e32 v8, v8
	v_exp_f32_e32 v9, v9
	v_and_b32_e32 v10, 0xffff0000, v44
	v_and_b32_e32 v11, 0xffff0000, v45
	v_lshlrev_b32_e32 v12, 16, v70
	v_and_b32_e32 v13, 0xffff0000, v70
	v_pk_fma_f32 v[4:5], v[4:5], v[8:9], v[10:11]
	v_mul_f32_e32 v12, v4, v12
	v_mul_f32_e32 v13, v5, v13
	v_cvt_pk_bf16_f32 v12, v12, v13
	global_store_dword v3, v12, s[18:19]
	s_add_u32 s18, s18, 0x1800
	s_addc_u32 s19, s19, 0
	s_waitcnt vmcnt(31)
	v_lshlrev_b32_e32 v16, 16, v46
	v_lshlrev_b32_e32 v17, 16, v47
	v_exp_f32_e32 v16, v16
	v_exp_f32_e32 v17, v17
	v_and_b32_e32 v18, 0xffff0000, v46
	v_and_b32_e32 v19, 0xffff0000, v47
	v_lshlrev_b32_e32 v20, 16, v71
	v_and_b32_e32 v21, 0xffff0000, v71
	v_pk_fma_f32 v[4:5], v[4:5], v[16:17], v[18:19]
	v_mul_f32_e32 v20, v4, v20
	v_mul_f32_e32 v21, v5, v21
	v_cvt_pk_bf16_f32 v20, v20, v21
	global_store_dword v3, v20, s[18:19]
	s_add_u32 s18, s18, 0x1800
	s_addc_u32 s19, s19, 0
	s_waitcnt vmcnt(29)
; __device__ __forceinline__ unsigned cvt_pk_bf16(float lo, float hi) { unsigned r; asm volatile("v_cvt_pk_bf16_f32 %0, %1, %2" : "=v"(r) : "v"(lo), "v"(hi)); return r; }
; __device__ __forceinline__ float bf_lo(unsigned w) { return __uint_as_float(w << 16); }
; __device__ __forceinline__ float bf_hi(unsigned w) { return __uint_as_float(w & 0xffff0000u); }
; __device__ __forceinline__ void xcd_barrier(const XcdBarrier& b) {
;     asm volatile("s_waitcnt vmcnt(0)" ::: "memory");
;     __syncthreads();
; __global__ void __launch_bounds__(NTHR, 2) hybrid_block_fwd(Args a) {
;     ...
;         for (int i = 0; i < CH_L; ++i) {
;             const u32x2 q = pab[(size_t)i * (LW / 2)]; const f32x2 av = (f32x2){__builtin_amdgcn_exp2f(bf_lo(q.x)), __builtin_amdgcn_exp2f(bf_lo(q.y))}, bv = (f32x2){bf_hi(q.x), bf_hi(q.y)}; const unsigned gq = pg[(size_t)i * (LW / 2)];
;             H = av * H + bv;
;             po[(size_t)i * (KC / 2)] = cvt_pk_bf16(H.x * bf_lo(gq), H.y * bf_hi(gq));
;         }
	v_lshlrev_b32_e32 v8, 16, v48
	v_lshlrev_b32_e32 v9, 16, v49
	v_exp_f32_e32 v8, v8
	v_exp_f32_e32 v9, v9
	v_and_b32_e32 v10, 0xffff0000, v48
	v_and_b32_e32 v11, 0xffff0000, v49
	v_lshlrev_b32_e32 v12, 16, v72
	v_and_b32_e32 v13, 0xffff0000, v72
	v_pk_fma_f32 v[4:5], v[4:5], v[8:9], v[10:11]
	v_mul_f32_e32 v12, v4, v12
	v_mul_f32_e32 v13, v5, v13
	v_cvt_pk_bf16_f32 v12, v12, v13
	global_store_dword v3, v12, s[18:19]
	s_add_u32 s18, s18, 0x1800
	s_addc_u32 s19, s19, 0
	s_waitcnt vmcnt(27)
	v_lshlrev_b32_e32 v16, 16, v50
	v_lshlrev_b32_e32 v17, 16, v51
	v_exp_f32_e32 v16, v16
	v_exp_f32_e32 v17, v17
	v_and_b32_e32 v18, 0xffff0000, v50
	v_and_b32_e32 v19, 0xffff0000, v51
	v_lshlrev_b32_e32 v20, 16, v73
	v_and_b32_e32 v21, 0xffff0000, v73
	v_pk_fma_f32 v[4:5], v[4:5], v[16:17], v[18:19]
	v_mul_f32_e32 v20, v4, v20
	v_mul_f32_e32 v21, v5, v21
	v_cvt_pk_bf16_f32 v20, v20, v21
	global_store_dword v3, v20, s[18:19]
	s_add_u32 s18, s18, 0x1800
	s_addc_u32 s19, s19, 0
	s_waitcnt vmcnt(25)
	v_lshlrev_b32_e32 v8, 16, v52
	v_lshlrev_b32_e32 v9, 16, v53
	v_exp_f32_e32 v8, v8
	v_exp_f32_e32 v9, v9
	v_and_b32_e32 v10, 0xffff0000, v52
	v_and_b32_e32 v11, 0xffff0000, v53
	v_lshlrev_b32_e32 v12, 16, v74
	v_and_b32_e32 v13, 0xffff0000, v74
	v_pk_fma_f32 v[4:5], v[4:5], v[8:9], v[10:11]
	v_mul_f32_e32 v12, v4, v12
	v_mul_f32_e32 v13, v5, v13
	v_cvt_pk_bf16_f32 v12, v12, v13
	global_store_dword v3, v12, s[18:19]
	s_add_u32 s18, s18, 0x1800
	s_addc_u32 s19, s19, 0
	s_waitcnt vmcnt(23)
	v_lshlrev_b32_e32 v16, 16, v54
	v_lshlrev_b32_e32 v17, 16, v55
	v_exp_f32_e32 v16, v16
	v_exp_f32_e32 v17, v17
	v_and_b32_e32 v18, 0xffff0000, v54
	v_and_b32_e32 v19, 0xffff0000, v55
	v_lshlrev_b32_e32 v20, 16, v75
	v_and_b32_e32 v21, 0xffff0000, v75
	v_pk_fma_f32 v[4:5], v[4:5], v[16:17], v[18:19]
	v_mul_f32_e32 v20, v4, v20
	v_mul_f32_e32 v21, v5, v21
	v_cvt_pk_bf16_f32 v20, v20, v21
	global_store_dword v3, v20, s[18:19]
	s_add_u32 s18, s18, 0x1800
	s_addc_u32 s19, s19, 0
	s_waitcnt vmcnt(21)
	v_lshlrev_b32_e32 v8, 16, v56
	v_lshlrev_b32_e32 v9, 16, v57
	v_exp_f32_e32 v8, v8
	v_exp_f32_e32 v9, v9
	v_and_b32_e32 v10, 0xffff0000, v56
	v_and_b32_e32 v11, 0xffff0000, v57
	v_lshlrev_b32_e32 v12, 16, v76
	v_and_b32_e32 v13, 0xffff0000, v76
	v_pk_fma_f32 v[4:5], v[4:5], v[8:9], v[10:11]
	v_mul_f32_e32 v12, v4, v12
	v_mul_f32_e32 v13, v5, v13
	v_cvt_pk_bf16_f32 v12, v12, v13
	global_store_dword v3, v12, s[18:19]
	s_add_u32 s18, s18, 0x1800
	s_addc_u32 s19, s19, 0
	s_waitcnt vmcnt(19)
	v_lshlrev_b32_e32 v16, 16, v58
	v_lshlrev_b32_e32 v17, 16, v59
	v_exp_f32_e32 v16, v16
	v_exp_f32_e32 v17, v17
	v_and_b32_e32 v18, 0xffff0000, v58
	v_and_b32_e32 v19, 0xffff0000, v59
	v_lshlrev_b32_e32 v20, 16, v77
	v_and_b32_e32 v21, 0xffff0000, v77
	v_pk_fma_f32 v[4:5], v[4:5], v[16:17], v[18:19]
	v_mul_f32_e32 v20, v4, v20
	v_mul_f32_e32 v21, v5, v21
	v_cvt_pk_bf16_f32 v20, v20, v21
	global_store_dword v3, v20, s[18:19]
	s_add_u32 s18, s18, 0x1800
	s_addc_u32 s19, s19, 0
	s_waitcnt vmcnt(17)
	v_lshlrev_b32_e32 v8, 16, v60
	v_lshlrev_b32_e32 v9, 16, v61
	v_exp_f32_e32 v8, v8
	v_exp_f32_e32 v9, v9
	v_and_b32_e32 v10, 0xffff0000, v60
	v_and_b32_e32 v11, 0xffff0000, v61
	v_lshlrev_b32_e32 v12, 16, v78
	v_and_b32_e32 v13, 0xffff0000, v78
	v_pk_fma_f32 v[4:5], v[4:5], v[8:9], v[10:11]
	v_mul_f32_e32 v12, v4, v12
	v_mul_f32_e32 v13, v5, v13
	v_cvt_pk_bf16_f32 v12, v12, v13
	global_store_dword v3, v12, s[18:19]
	s_add_u32 s18, s18, 0x1800
	s_addc_u32 s19, s19, 0
	s_waitcnt vmcnt(15)
	v_lshlrev_b32_e32 v16, 16, v62
	v_lshlrev_b32_e32 v17, 16, v63
	v_exp_f32_e32 v16, v16
	v_exp_f32_e32 v17, v17
	v_and_b32_e32 v18, 0xffff0000, v62
	v_and_b32_e32 v19, 0xffff0000, v63
	v_lshlrev_b32_e32 v20, 16, v79
	v_and_b32_e32 v21, 0xffff0000, v79
	v_pk_fma_f32 v[4:5], v[4:5], v[16:17], v[18:19]
	v_mul_f32_e32 v20, v4, v20
	v_mul_f32_e32 v21, v5, v21
	v_cvt_pk_bf16_f32 v20, v20, v21
	global_store_dword v3, v20, s[18:19]
	s_add_u32 s18, s18, 0x1800
	s_addc_u32 s19, s19, 0
	s_waitcnt vmcnt(0)
	s_barrier
	v_readfirstlane_b32 s0, v212
	s_cmp_lg_u32 s0, 64
	s_cbranch_scc1 .Linv_4
	s_sleep 48
	buffer_inv sc1
	s_waitcnt vmcnt(0)

; __device__ __forceinline__ void xcd_barrier(const XcdBarrier& b) {
;     asm volatile("s_waitcnt vmcnt(0)" ::: "memory");
;     __syncthreads();
;     ...
;             __builtin_amdgcn_fence(__ATOMIC_ACQUIRE, "agent");
;             asm volatile("s_waitcnt vmcnt(0)" ::: "memory");
.Lp5_tr_done:
	s_add_u32 s27, s94, 0x10f00000
	s_addc_u32 s28, s95, 0
	s_waitcnt vmcnt(0)
	v_readlane_b32 s72, v248, 6
	v_readlane_b32 s73, v248, 7
	s_waitcnt lgkmcnt(0)
	s_barrier
	v_readfirstlane_b32 s0, v212
	s_cmp_lg_u32 s0, 64
	s_cbranch_scc1 .Linv_6
	s_sleep 48
	buffer_inv sc1
	s_waitcnt vmcnt(0)

; __device__ __forceinline__ void xcd_barrier(const XcdBarrier& b) {
;     asm volatile("s_waitcnt vmcnt(0)" ::: "memory");
;     __syncthreads();
;     ...
;             __builtin_amdgcn_fence(__ATOMIC_ACQUIRE, "agent");
;             asm volatile("s_waitcnt vmcnt(0)" ::: "memory");
.LBB0_949:
	s_waitcnt vmcnt(0)
	s_barrier
	s_waitcnt vmcnt(0)
	s_barrier
	v_readfirstlane_b32 s0, v212
	s_cmp_lg_u32 s0, 64
	s_cbranch_scc1 .Linv_7
	s_sleep 48
	buffer_inv sc1
	s_waitcnt vmcnt(0)

; __device__ __forceinline__ unsigned cvt_pk_bf16(float lo, float hi) { unsigned r; asm volatile("v_cvt_pk_bf16_f32 %0, %1, %2" : "=v"(r) : "v"(lo), "v"(hi)); return r; }
; __global__ void __launch_bounds__(NTHR, 2) hybrid_block_fwd(Args a) {
;     ...
;         for (int idx = gtid; idx < 256 * 2 * (FF / 4); idx += NT) {
;             const int f4 = (idx % (FF / 4)) * 4, rr = (idx / (FF / 4)) & 1, blk = idx / (2 * (FF / 4));
;             const bool seq0 = (blk & 127) == 0; const size_t row = (size_t)blk * 64 + rr;
;             const f32x4 z = (f32x4){0.f, 0.f, 0.f, 0.f};
;             const f32x4 gc = *(const f32x4*)(HEADG + ((size_t)blk * 2 + rr) * FF + f4), vv = *(const f32x4*)(HEADV + ((size_t)blk * 2 + rr) * FF + f4);
;             f32x4 p1, p2;
;             if (rr == 0) { p1 = seq0 ? z : *(const f32x4*)(TAILG + ((size_t)(blk - 1) * 2 + 1) * FF + f4); p2 = seq0 ? z : *(const f32x4*)(TAILG + ((size_t)(blk - 1) * 2 + 0) * FF + f4); }
;             else { p1 = *(const f32x4*)(HEADG + ((size_t)blk * 2 + 0) * FF + f4); p2 = seq0 ? z : *(const f32x4*)(TAILG + ((size_t)(blk - 1) * 2 + 1) * FF + f4); }
;             const f32x4 cv = *(const f32x4*)(ffn_conv_b + f4) + *(const f32x4*)(ffn_conv_w + f4) * p2 + *(const f32x4*)(ffn_conv_w + FF + f4) * p1 + *(const f32x4*)(ffn_conv_w + 2 * FF + f4) * gc;
;             u32x2 w; w.x = cvt_pk_bf16(gelu_tanh(cv[0]) * vv[0], gelu_tanh(cv[1]) * vv[1]); w.y = cvt_pk_bf16(gelu_tanh(cv[2]) * vv[2], gelu_tanh(cv[3]) * vv[3]);
;             *(u32x2*)(ACT + row * FF + f4) = w;
;         }
.LBB0_1002:
	s_or_b64 exec, exec, s[0:1]
	s_waitcnt lgkmcnt(0)
	v_mov_b32_e32 v0, v212
	v_readlane_b32 s0, v248, 8
	s_barrier
	s_mov_b64 s[4:5], exec
	v_add_u32_e32 v1, s0, v0
	s_mov_b32 s6, 0x2aaaaaab
	v_mul_hi_i32 v2, v1, s6
	v_ashrrev_i32_e32 v3, 8, v2
	v_lshlrev_b32_e32 v4, 4, v1
	v_mul_u32_u24_e32 v5, 0x6000, v3
	v_sub_u32_e32 v4, v4, v5
	v_mov_b32_e32 v49, v3
	v_add_u32_e32 v6, v5, v4
	v_add_u32_e32 v7, 0x2700000, v6
	global_load_dwordx4 v[16:19], v7, s[94:95]
	v_add_u32_e32 v7, 0x3300000, v6
	global_load_dwordx4 v[20:23], v7, s[94:95]
	v_and_b32_e32 v8, 1, v3
	v_max_i32_e32 v9, 1, v3
	v_add_u32_e32 v9, -1, v9
	v_mul_u32_u24_e32 v9, 0x6000, v9
	v_add_u32_e32 v9, v9, v4
	v_cmp_eq_u32_e32 vcc, 1, v8
	v_mov_b32_e32 v7, 0x1b00000
	v_mov_b32_e32 v5, 0x2700000
	v_cndmask_b32_e32 v7, v7, v5, vcc
	v_add_u32_e32 v7, v7, v9
	global_load_dwordx4 v[24:27], v7, s[94:95]
	v_max_i32_e32 v9, 2, v3
	v_add_u32_e32 v9, -2, v9
	v_mul_u32_u24_e32 v9, 0x6000, v9
	v_add_u32_e32 v9, v9, v4
	v_add_u32_e32 v9, 0x1b00000, v9
	global_load_dwordx4 v[28:31], v9, s[94:95]
	global_load_dwordx4 v[32:35], v4, s[86:87]
	global_load_dwordx4 v[36:39], v4, s[84:85]
	global_load_dwordx4 v[40:43], v4, s[16:17]
	global_load_dwordx4 v[44:47], v4, s[18:19]
	v_lshrrev_b32_e32 v5, 1, v3
	v_lshl_or_b32 v5, v5, 6, v8
	v_mul_u32_u24_e32 v5, 0x3000, v5
	v_lshrrev_b32_e32 v7, 1, v4
	v_add_u32_e32 v5, v5, v7
	v_add_u32_e32 v48, 0x12700000, v5
	v_add_u32_e32 v1, 0x20000, v1
	v_mul_hi_i32 v2, v1, s6
	v_ashrrev_i32_e32 v3, 8, v2
	v_lshlrev_b32_e32 v4, 4, v1
	v_mul_u32_u24_e32 v5, 0x6000, v3
	v_sub_u32_e32 v4, v4, v5
	v_mov_b32_e32 v85, v3
	v_add_u32_e32 v6, v5, v4
	v_add_u32_e32 v7, 0x2700000, v6
	global_load_dwordx4 v[52:55], v7, s[94:95]
	v_add_u32_e32 v7, 0x3300000, v6
	global_load_dwordx4 v[56:59], v7, s[94:95]
	v_and_b32_e32 v8, 1, v3
	v_max_i32_e32 v9, 1, v3
	v_add_u32_e32 v9, -1, v9
	v_mul_u32_u24_e32 v9, 0x6000, v9
	v_add_u32_e32 v9, v9, v4
	v_cmp_eq_u32_e32 vcc, 1, v8
	v_mov_b32_e32 v7, 0x1b00000
	v_mov_b32_e32 v5, 0x2700000
	v_cndmask_b32_e32 v7, v7, v5, vcc
	v_add_u32_e32 v7, v7, v9
	global_load_dwordx4 v[60:63], v7, s[94:95]
	v_max_i32_e32 v9, 2, v3
	v_add_u32_e32 v9, -2, v9
	v_mul_u32_u24_e32 v9, 0x6000, v9
	v_add_u32_e32 v9, v9, v4
	v_add_u32_e32 v9, 0x1b00000, v9
	global_load_dwordx4 v[64:67], v9, s[94:95]
	global_load_dwordx4 v[68:71], v4, s[86:87]
	global_load_dwordx4 v[72:75], v4, s[84:85]
	global_load_dwordx4 v[76:79], v4, s[16:17]
	global_load_dwordx4 v[80:83], v4, s[18:19]
	v_lshrrev_b32_e32 v5, 1, v3
	v_lshl_or_b32 v5, v5, 6, v8
	v_mul_u32_u24_e32 v5, 0x3000, v5
	v_lshrrev_b32_e32 v7, 1, v4
	v_add_u32_e32 v5, v5, v7
	v_add_u32_e32 v84, 0x12700000, v5
	v_add_u32_e32 v1, 0x20000, v1
	v_mul_hi_i32 v2, v1, s6
	v_ashrrev_i32_e32 v3, 8, v2
	v_lshlrev_b32_e32 v4, 4, v1
	v_mul_u32_u24_e32 v5, 0x6000, v3
	v_sub_u32_e32 v4, v4, v5
	v_mov_b32_e32 v121, v3
	v_add_u32_e32 v6, v5, v4
	v_add_u32_e32 v7, 0x2700000, v6
	global_load_dwordx4 v[88:91], v7, s[94:95]
	v_add_u32_e32 v7, 0x3300000, v6
	global_load_dwordx4 v[92:95], v7, s[94:95]
	v_and_b32_e32 v8, 1, v3
	v_max_i32_e32 v9, 1, v3
	v_add_u32_e32 v9, -1, v9
	v_mul_u32_u24_e32 v9, 0x6000, v9
	v_add_u32_e32 v9, v9, v4
	v_cmp_eq_u32_e32 vcc, 1, v8
	v_mov_b32_e32 v7, 0x1b00000
	v_mov_b32_e32 v5, 0x2700000
	v_cndmask_b32_e32 v7, v7, v5, vcc
	v_add_u32_e32 v7, v7, v9
	global_load_dwordx4 v[96:99], v7, s[94:95]
	v_max_i32_e32 v9, 2, v3
	v_add_u32_e32 v9, -2, v9
	v_mul_u32_u24_e32 v9, 0x6000, v9
	v_add_u32_e32 v9, v9, v4
	v_add_u32_e32 v9, 0x1b00000, v9
	global_load_dwordx4 v[100:103], v9, s[94:95]
	global_load_dwordx4 v[104:107], v4, s[86:87]
	global_load_dwordx4 v[108:111], v4, s[84:85]
	global_load_dwordx4 v[112:115], v4, s[16:17]
	global_load_dwordx4 v[116:119], v4, s[18:19]
	v_lshrrev_b32_e32 v5, 1, v3
	v_lshl_or_b32 v5, v5, 6, v8
	v_mul_u32_u24_e32 v5, 0x3000, v5
	v_lshrrev_b32_e32 v7, 1, v4
	v_add_u32_e32 v5, v5, v7
	v_add_u32_e32 v120, 0x12700000, v5
	v_add_u32_e32 v1, 0x20000, v1
	s_waitcnt vmcnt(16)
	v_lshrrev_b32_e32 v2, 1, v49
	v_and_b32_e32 v2, 0x7f, v2
	v_cmp_eq_u32_e32 vcc, 0, v2
	v_and_b32_e32 v3, 1, v49
	v_cmp_eq_u32_e64 s[8:9], 0, v3
	s_nop 1
	s_and_b64 s[8:9], s[8:9], vcc
	s_nop 1
	v_cndmask_b32_e64 v28, v28, 0, vcc
	v_cndmask_b32_e64 v24, v24, 0, s[8:9]
	v_cndmask_b32_e64 v29, v29, 0, vcc
	v_cndmask_b32_e64 v25, v25, 0, s[8:9]
	v_cndmask_b32_e64 v30, v30, 0, vcc
	v_cndmask_b32_e64 v26, v26, 0, s[8:9]
	v_cndmask_b32_e64 v31, v31, 0, vcc
	v_cndmask_b32_e64 v27, v27, 0, s[8:9]
	v_pk_fma_f32 v[30:31], v[30:31], v[38:39], v[34:35]
	v_pk_fma_f32 v[28:29], v[28:29], v[36:37], v[32:33]
	v_pk_fma_f32 v[26:27], v[26:27], v[42:43], v[30:31]
	v_pk_fma_f32 v[24:25], v[24:25], v[40:41], v[28:29]
	v_pk_fma_f32 v[18:19], v[18:19], v[46:47], v[26:27]
	v_pk_fma_f32 v[16:17], v[16:17], v[44:45], v[24:25]
	v_mul_f32_e32 v32, 0x3d922279, v16
	v_mul_f32_e32 v33, 0x3d922279, v17
	v_mul_f32_e32 v34, 0x3d922279, v18
	v_mul_f32_e32 v35, 0x3d922279, v19
	v_fmaak_f32 v32, v16, v32, 0x3fcc422a
	v_fmaak_f32 v33, v17, v33, 0x3fcc422a
	v_fmaak_f32 v34, v18, v34, 0x3fcc422a
	v_fmaak_f32 v35, v19, v35, 0x3fcc422a
	v_mul_f32_e32 v32, v16, v32
	v_mul_f32_e32 v33, v17, v33
	v_mul_f32_e32 v34, v18, v34
	v_mul_f32_e32 v35, v19, v35
	v_mul_f32_e32 v32, 0xbfb8aa3b, v32
	v_mul_f32_e32 v33, 0xbfb8aa3b, v33
	v_mul_f32_e32 v34, 0xbfb8aa3b, v34
	v_mul_f32_e32 v35, 0xbfb8aa3b, v35
	v_exp_f32_e32 v32, v32
	v_exp_f32_e32 v33, v33
	v_exp_f32_e32 v34, v34
	v_exp_f32_e32 v35, v35
	v_add_f32_e32 v32, 1.0, v32
	v_add_f32_e32 v33, 1.0, v33
	v_add_f32_e32 v34, 1.0, v34
	v_add_f32_e32 v35, 1.0, v35
	v_rcp_f32_e32 v32, v32
	v_rcp_f32_e32 v33, v33
	v_rcp_f32_e32 v34, v34
	v_rcp_f32_e32 v35, v35
	v_mul_f32_e32 v16, v16, v32
	v_mul_f32_e32 v17, v17, v33
	v_mul_f32_e32 v18, v18, v34
	v_mul_f32_e32 v19, v19, v35
	v_mul_f32_e32 v16, v20, v16
	v_mul_f32_e32 v17, v21, v17
	v_mul_f32_e32 v18, v22, v18
	v_mul_f32_e32 v19, v23, v19
	v_cvt_pk_bf16_f32 v16, v16, v17
	v_cvt_pk_bf16_f32 v17, v18, v19
	global_store_dwordx2 v48, v[16:17], s[94:95] sc1
	s_waitcnt vmcnt(9)
; __device__ __forceinline__ unsigned cvt_pk_bf16(float lo, float hi) { unsigned r; asm volatile("v_cvt_pk_bf16_f32 %0, %1, %2" : "=v"(r) : "v"(lo), "v"(hi)); return r; }
; __global__ void __launch_bounds__(NTHR, 2) hybrid_block_fwd(Args a) {
;     ...
;         for (int idx = gtid; idx < 256 * 2 * (FF / 4); idx += NT) {
;             const int f4 = (idx % (FF / 4)) * 4, rr = (idx / (FF / 4)) & 1, blk = idx / (2 * (FF / 4));
;             const bool seq0 = (blk & 127) == 0; const size_t row = (size_t)blk * 64 + rr;
;             const f32x4 z = (f32x4){0.f, 0.f, 0.f, 0.f};
;             const f32x4 gc = *(const f32x4*)(HEADG + ((size_t)blk * 2 + rr) * FF + f4), vv = *(const f32x4*)(HEADV + ((size_t)blk * 2 + rr) * FF + f4);
;             f32x4 p1, p2;
;             if (rr == 0) { p1 = seq0 ? z : *(const f32x4*)(TAILG + ((size_t)(blk - 1) * 2 + 1) * FF + f4); p2 = seq0 ? z : *(const f32x4*)(TAILG + ((size_t)(blk - 1) * 2 + 0) * FF + f4); }
;             else { p1 = *(const f32x4*)(HEADG + ((size_t)blk * 2 + 0) * FF + f4); p2 = seq0 ? z : *(const f32x4*)(TAILG + ((size_t)(blk - 1) * 2 + 1) * FF + f4); }
;             const f32x4 cv = *(const f32x4*)(ffn_conv_b + f4) + *(const f32x4*)(ffn_conv_w + f4) * p2 + *(const f32x4*)(ffn_conv_w + FF + f4) * p1 + *(const f32x4*)(ffn_conv_w + 2 * FF + f4) * gc;
;             u32x2 w; w.x = cvt_pk_bf16(gelu_tanh(cv[0]) * vv[0], gelu_tanh(cv[1]) * vv[1]); w.y = cvt_pk_bf16(gelu_tanh(cv[2]) * vv[2], gelu_tanh(cv[3]) * vv[3]);
;             *(u32x2*)(ACT + row * FF + f4) = w;
;         }
	v_lshrrev_b32_e32 v2, 1, v85
	v_and_b32_e32 v2, 0x7f, v2
	v_cmp_eq_u32_e32 vcc, 0, v2
	v_and_b32_e32 v3, 1, v85
	v_cmp_eq_u32_e64 s[8:9], 0, v3
	s_nop 1
	s_and_b64 s[8:9], s[8:9], vcc
	s_nop 1
	v_cndmask_b32_e64 v64, v64, 0, vcc
	v_cndmask_b32_e64 v60, v60, 0, s[8:9]
	v_cndmask_b32_e64 v65, v65, 0, vcc
	v_cndmask_b32_e64 v61, v61, 0, s[8:9]
	v_cndmask_b32_e64 v66, v66, 0, vcc
	v_cndmask_b32_e64 v62, v62, 0, s[8:9]
	v_cndmask_b32_e64 v67, v67, 0, vcc
	v_cndmask_b32_e64 v63, v63, 0, s[8:9]
	v_pk_fma_f32 v[66:67], v[66:67], v[74:75], v[70:71]
	v_pk_fma_f32 v[64:65], v[64:65], v[72:73], v[68:69]
	v_pk_fma_f32 v[62:63], v[62:63], v[78:79], v[66:67]
	v_pk_fma_f32 v[60:61], v[60:61], v[76:77], v[64:65]
	v_pk_fma_f32 v[54:55], v[54:55], v[82:83], v[62:63]
	v_pk_fma_f32 v[52:53], v[52:53], v[80:81], v[60:61]
	v_mul_f32_e32 v68, 0x3d922279, v52
	v_mul_f32_e32 v69, 0x3d922279, v53
	v_mul_f32_e32 v70, 0x3d922279, v54
	v_mul_f32_e32 v71, 0x3d922279, v55
	v_fmaak_f32 v68, v52, v68, 0x3fcc422a
	v_fmaak_f32 v69, v53, v69, 0x3fcc422a
	v_fmaak_f32 v70, v54, v70, 0x3fcc422a
	v_fmaak_f32 v71, v55, v71, 0x3fcc422a
	v_mul_f32_e32 v68, v52, v68
	v_mul_f32_e32 v69, v53, v69
	v_mul_f32_e32 v70, v54, v70
	v_mul_f32_e32 v71, v55, v71
	v_mul_f32_e32 v68, 0xbfb8aa3b, v68
	v_mul_f32_e32 v69, 0xbfb8aa3b, v69
	v_mul_f32_e32 v70, 0xbfb8aa3b, v70
	v_mul_f32_e32 v71, 0xbfb8aa3b, v71
	v_exp_f32_e32 v68, v68
	v_exp_f32_e32 v69, v69
	v_exp_f32_e32 v70, v70
	v_exp_f32_e32 v71, v71
	v_add_f32_e32 v68, 1.0, v68
	v_add_f32_e32 v69, 1.0, v69
	v_add_f32_e32 v70, 1.0, v70
	v_add_f32_e32 v71, 1.0, v71
	v_rcp_f32_e32 v68, v68
	v_rcp_f32_e32 v69, v69
	v_rcp_f32_e32 v70, v70
	v_rcp_f32_e32 v71, v71
	v_mul_f32_e32 v52, v52, v68
	v_mul_f32_e32 v53, v53, v69
	v_mul_f32_e32 v54, v54, v70
	v_mul_f32_e32 v55, v55, v71
	v_mul_f32_e32 v52, v56, v52
	v_mul_f32_e32 v53, v57, v53
	v_mul_f32_e32 v54, v58, v54
	v_mul_f32_e32 v55, v59, v55
	v_cvt_pk_bf16_f32 v52, v52, v53
	v_cvt_pk_bf16_f32 v53, v54, v55
	global_store_dwordx2 v84, v[52:53], s[94:95] sc1
	s_waitcnt vmcnt(2)
	v_lshrrev_b32_e32 v2, 1, v121
	v_and_b32_e32 v2, 0x7f, v2
	v_cmp_eq_u32_e32 vcc, 0, v2
	v_and_b32_e32 v3, 1, v121
	v_cmp_eq_u32_e64 s[8:9], 0, v3
	s_nop 1
	s_and_b64 s[8:9], s[8:9], vcc
	s_nop 1
	v_cndmask_b32_e64 v100, v100, 0, vcc
	v_cndmask_b32_e64 v96, v96, 0, s[8:9]
	v_cndmask_b32_e64 v101, v101, 0, vcc
	v_cndmask_b32_e64 v97, v97, 0, s[8:9]
	v_cndmask_b32_e64 v102, v102, 0, vcc
	v_cndmask_b32_e64 v98, v98, 0, s[8:9]
	v_cndmask_b32_e64 v103, v103, 0, vcc
	v_cndmask_b32_e64 v99, v99, 0, s[8:9]
	v_pk_fma_f32 v[102:103], v[102:103], v[110:111], v[106:107]
	v_pk_fma_f32 v[100:101], v[100:101], v[108:109], v[104:105]
	v_pk_fma_f32 v[98:99], v[98:99], v[114:115], v[102:103]
	v_pk_fma_f32 v[96:97], v[96:97], v[112:113], v[100:101]
	v_pk_fma_f32 v[90:91], v[90:91], v[118:119], v[98:99]
	v_pk_fma_f32 v[88:89], v[88:89], v[116:117], v[96:97]
	v_mul_f32_e32 v104, 0x3d922279, v88
	v_mul_f32_e32 v105, 0x3d922279, v89
	v_mul_f32_e32 v106, 0x3d922279, v90
	v_mul_f32_e32 v107, 0x3d922279, v91
	v_fmaak_f32 v104, v88, v104, 0x3fcc422a
	v_fmaak_f32 v105, v89, v105, 0x3fcc422a
	v_fmaak_f32 v106, v90, v106, 0x3fcc422a
	v_fmaak_f32 v107, v91, v107, 0x3fcc422a
	v_mul_f32_e32 v104, v88, v104
	v_mul_f32_e32 v105, v89, v105
	v_mul_f32_e32 v106, v90, v106
	v_mul_f32_e32 v107, v91, v107
	v_mul_f32_e32 v104, 0xbfb8aa3b, v104
	v_mul_f32_e32 v105, 0xbfb8aa3b, v105
	v_mul_f32_e32 v106, 0xbfb8aa3b, v106
	v_mul_f32_e32 v107, 0xbfb8aa3b, v107
	v_exp_f32_e32 v104, v104
	v_exp_f32_e32 v105, v105
	v_exp_f32_e32 v106, v106
	v_exp_f32_e32 v107, v107
	v_add_f32_e32 v104, 1.0, v104
	v_add_f32_e32 v105, 1.0, v105
	v_add_f32_e32 v106, 1.0, v106
	v_add_f32_e32 v107, 1.0, v107
	v_rcp_f32_e32 v104, v104
	v_rcp_f32_e32 v105, v105
	v_rcp_f32_e32 v106, v106
	v_rcp_f32_e32 v107, v107
	v_mul_f32_e32 v88, v88, v104
	v_mul_f32_e32 v89, v89, v105
	v_mul_f32_e32 v90, v90, v106
	v_mul_f32_e32 v91, v91, v107
	v_mul_f32_e32 v88, v92, v88
	v_mul_f32_e32 v89, v93, v89
	v_mul_f32_e32 v90, v94, v90
	v_mul_f32_e32 v91, v95, v91
	v_cvt_pk_bf16_f32 v88, v88, v89
	v_cvt_pk_bf16_f32 v89, v90, v91
	global_store_dwordx2 v120, v[88:89], s[94:95] sc1
	v_mul_hi_i32 v2, v1, s6
	v_ashrrev_i32_e32 v3, 8, v2
	v_lshlrev_b32_e32 v4, 4, v1
	v_mul_u32_u24_e32 v5, 0x6000, v3
	v_sub_u32_e32 v4, v4, v5
	v_mov_b32_e32 v49, v3
	v_add_u32_e32 v6, v5, v4
	v_add_u32_e32 v7, 0x2700000, v6
	global_load_dwordx4 v[16:19], v7, s[94:95]
	v_add_u32_e32 v7, 0x3300000, v6
	global_load_dwordx4 v[20:23], v7, s[94:95]
	v_and_b32_e32 v8, 1, v3
	v_max_i32_e32 v9, 1, v3
	v_add_u32_e32 v9, -1, v9
	v_mul_u32_u24_e32 v9, 0x6000, v9
	v_add_u32_e32 v9, v9, v4
	v_cmp_eq_u32_e32 vcc, 1, v8
	v_mov_b32_e32 v7, 0x1b00000
	v_mov_b32_e32 v5, 0x2700000
	v_cndmask_b32_e32 v7, v7, v5, vcc
	v_add_u32_e32 v7, v7, v9
	global_load_dwordx4 v[24:27], v7, s[94:95]
	v_max_i32_e32 v9, 2, v3
	v_add_u32_e32 v9, -2, v9
	v_mul_u32_u24_e32 v9, 0x6000, v9
	v_add_u32_e32 v9, v9, v4
	v_add_u32_e32 v9, 0x1b00000, v9
	global_load_dwordx4 v[28:31], v9, s[94:95]
	global_load_dwordx4 v[32:35], v4, s[86:87]
	global_load_dwordx4 v[36:39], v4, s[84:85]
	global_load_dwordx4 v[40:43], v4, s[16:17]
	global_load_dwordx4 v[44:47], v4, s[18:19]
	v_lshrrev_b32_e32 v5, 1, v3
	v_lshl_or_b32 v5, v5, 6, v8
	v_mul_u32_u24_e32 v5, 0x3000, v5
	v_lshrrev_b32_e32 v7, 1, v4
	v_add_u32_e32 v5, v5, v7
	v_add_u32_e32 v48, 0x12700000, v5
	v_add_u32_e32 v1, 0x20000, v1
	v_mul_hi_i32 v2, v1, s6
	v_ashrrev_i32_e32 v3, 8, v2
	v_lshlrev_b32_e32 v4, 4, v1
	v_mul_u32_u24_e32 v5, 0x6000, v3
	v_sub_u32_e32 v4, v4, v5
	v_mov_b32_e32 v85, v3
	v_add_u32_e32 v6, v5, v4
	v_add_u32_e32 v7, 0x2700000, v6
; __device__ __forceinline__ unsigned cvt_pk_bf16(float lo, float hi) { unsigned r; asm volatile("v_cvt_pk_bf16_f32 %0, %1, %2" : "=v"(r) : "v"(lo), "v"(hi)); return r; }
; __global__ void __launch_bounds__(NTHR, 2) hybrid_block_fwd(Args a) {
;     ...
;         for (int idx = gtid; idx < 256 * 2 * (FF / 4); idx += NT) {
;             const int f4 = (idx % (FF / 4)) * 4, rr = (idx / (FF / 4)) & 1, blk = idx / (2 * (FF / 4));
;             const bool seq0 = (blk & 127) == 0; const size_t row = (size_t)blk * 64 + rr;
;             const f32x4 z = (f32x4){0.f, 0.f, 0.f, 0.f};
;             const f32x4 gc = *(const f32x4*)(HEADG + ((size_t)blk * 2 + rr) * FF + f4), vv = *(const f32x4*)(HEADV + ((size_t)blk * 2 + rr) * FF + f4);
;             f32x4 p1, p2;
;             if (rr == 0) { p1 = seq0 ? z : *(const f32x4*)(TAILG + ((size_t)(blk - 1) * 2 + 1) * FF + f4); p2 = seq0 ? z : *(const f32x4*)(TAILG + ((size_t)(blk - 1) * 2 + 0) * FF + f4); }
;             else { p1 = *(const f32x4*)(HEADG + ((size_t)blk * 2 + 0) * FF + f4); p2 = seq0 ? z : *(const f32x4*)(TAILG + ((size_t)(blk - 1) * 2 + 1) * FF + f4); }
;             const f32x4 cv = *(const f32x4*)(ffn_conv_b + f4) + *(const f32x4*)(ffn_conv_w + f4) * p2 + *(const f32x4*)(ffn_conv_w + FF + f4) * p1 + *(const f32x4*)(ffn_conv_w + 2 * FF + f4) * gc;
;             u32x2 w; w.x = cvt_pk_bf16(gelu_tanh(cv[0]) * vv[0], gelu_tanh(cv[1]) * vv[1]); w.y = cvt_pk_bf16(gelu_tanh(cv[2]) * vv[2], gelu_tanh(cv[3]) * vv[3]);
;             *(u32x2*)(ACT + row * FF + f4) = w;
;         }
	global_load_dwordx4 v[52:55], v7, s[94:95]
	v_add_u32_e32 v7, 0x3300000, v6
	global_load_dwordx4 v[56:59], v7, s[94:95]
	v_and_b32_e32 v8, 1, v3
	v_max_i32_e32 v9, 1, v3
	v_add_u32_e32 v9, -1, v9
	v_mul_u32_u24_e32 v9, 0x6000, v9
	v_add_u32_e32 v9, v9, v4
	v_cmp_eq_u32_e32 vcc, 1, v8
	v_mov_b32_e32 v7, 0x1b00000
	v_mov_b32_e32 v5, 0x2700000
	v_cndmask_b32_e32 v7, v7, v5, vcc
	v_add_u32_e32 v7, v7, v9
	global_load_dwordx4 v[60:63], v7, s[94:95]
	v_max_i32_e32 v9, 2, v3
	v_add_u32_e32 v9, -2, v9
	v_mul_u32_u24_e32 v9, 0x6000, v9
	v_add_u32_e32 v9, v9, v4
	v_add_u32_e32 v9, 0x1b00000, v9
	global_load_dwordx4 v[64:67], v9, s[94:95]
	global_load_dwordx4 v[68:71], v4, s[86:87]
	global_load_dwordx4 v[72:75], v4, s[84:85]
	global_load_dwordx4 v[76:79], v4, s[16:17]
	global_load_dwordx4 v[80:83], v4, s[18:19]
	v_lshrrev_b32_e32 v5, 1, v3
	v_lshl_or_b32 v5, v5, 6, v8
	v_mul_u32_u24_e32 v5, 0x3000, v5
	v_lshrrev_b32_e32 v7, 1, v4
	v_add_u32_e32 v5, v5, v7
	v_add_u32_e32 v84, 0x12700000, v5
	v_add_u32_e32 v1, 0x20000, v1
	v_mul_hi_i32 v2, v1, s6
	v_ashrrev_i32_e32 v3, 8, v2
	v_lshlrev_b32_e32 v4, 4, v1
	v_mul_u32_u24_e32 v5, 0x6000, v3
	v_sub_u32_e32 v4, v4, v5
	v_mov_b32_e32 v121, v3
	v_add_u32_e32 v6, v5, v4
	v_add_u32_e32 v7, 0x2700000, v6
	global_load_dwordx4 v[88:91], v7, s[94:95]
	v_add_u32_e32 v7, 0x3300000, v6
	global_load_dwordx4 v[92:95], v7, s[94:95]
	v_and_b32_e32 v8, 1, v3
	v_max_i32_e32 v9, 1, v3
	v_add_u32_e32 v9, -1, v9
	v_mul_u32_u24_e32 v9, 0x6000, v9
	v_add_u32_e32 v9, v9, v4
	v_cmp_eq_u32_e32 vcc, 1, v8
	v_mov_b32_e32 v7, 0x1b00000
	v_mov_b32_e32 v5, 0x2700000
	v_cndmask_b32_e32 v7, v7, v5, vcc
	v_add_u32_e32 v7, v7, v9
	global_load_dwordx4 v[96:99], v7, s[94:95]
	v_max_i32_e32 v9, 2, v3
	v_add_u32_e32 v9, -2, v9
	v_mul_u32_u24_e32 v9, 0x6000, v9
	v_add_u32_e32 v9, v9, v4
	v_add_u32_e32 v9, 0x1b00000, v9
	global_load_dwordx4 v[100:103], v9, s[94:95]
	global_load_dwordx4 v[104:107], v4, s[86:87]
	global_load_dwordx4 v[108:111], v4, s[84:85]
	global_load_dwordx4 v[112:115], v4, s[16:17]
	global_load_dwordx4 v[116:119], v4, s[18:19]
	v_lshrrev_b32_e32 v5, 1, v3
	v_lshl_or_b32 v5, v5, 6, v8
	v_mul_u32_u24_e32 v5, 0x3000, v5
	v_lshrrev_b32_e32 v7, 1, v4
	v_add_u32_e32 v5, v5, v7
	v_add_u32_e32 v120, 0x12700000, v5
	v_add_u32_e32 v1, 0x20000, v1
	s_waitcnt vmcnt(16)
	v_lshrrev_b32_e32 v2, 1, v49
	v_and_b32_e32 v2, 0x7f, v2
	v_cmp_eq_u32_e32 vcc, 0, v2
	v_and_b32_e32 v3, 1, v49
	v_cmp_eq_u32_e64 s[8:9], 0, v3
	s_nop 1
	s_and_b64 s[8:9], s[8:9], vcc
	s_nop 1
	v_cndmask_b32_e64 v28, v28, 0, vcc
	v_cndmask_b32_e64 v24, v24, 0, s[8:9]
	v_cndmask_b32_e64 v29, v29, 0, vcc
	v_cndmask_b32_e64 v25, v25, 0, s[8:9]
	v_cndmask_b32_e64 v30, v30, 0, vcc
	v_cndmask_b32_e64 v26, v26, 0, s[8:9]
	v_cndmask_b32_e64 v31, v31, 0, vcc
	v_cndmask_b32_e64 v27, v27, 0, s[8:9]
	v_pk_fma_f32 v[30:31], v[30:31], v[38:39], v[34:35]
	v_pk_fma_f32 v[28:29], v[28:29], v[36:37], v[32:33]
	v_pk_fma_f32 v[26:27], v[26:27], v[42:43], v[30:31]
	v_pk_fma_f32 v[24:25], v[24:25], v[40:41], v[28:29]
	v_pk_fma_f32 v[18:19], v[18:19], v[46:47], v[26:27]
	v_pk_fma_f32 v[16:17], v[16:17], v[44:45], v[24:25]
	v_mul_f32_e32 v32, 0x3d922279, v16
	v_mul_f32_e32 v33, 0x3d922279, v17
	v_mul_f32_e32 v34, 0x3d922279, v18
	v_mul_f32_e32 v35, 0x3d922279, v19
	v_fmaak_f32 v32, v16, v32, 0x3fcc422a
	v_fmaak_f32 v33, v17, v33, 0x3fcc422a
	v_fmaak_f32 v34, v18, v34, 0x3fcc422a
	v_fmaak_f32 v35, v19, v35, 0x3fcc422a
	v_mul_f32_e32 v32, v16, v32
	v_mul_f32_e32 v33, v17, v33
	v_mul_f32_e32 v34, v18, v34
	v_mul_f32_e32 v35, v19, v35
	v_mul_f32_e32 v32, 0xbfb8aa3b, v32
	v_mul_f32_e32 v33, 0xbfb8aa3b, v33
	v_mul_f32_e32 v34, 0xbfb8aa3b, v34
	v_mul_f32_e32 v35, 0xbfb8aa3b, v35
	v_exp_f32_e32 v32, v32
	v_exp_f32_e32 v33, v33
	v_exp_f32_e32 v34, v34
	v_exp_f32_e32 v35, v35
	v_add_f32_e32 v32, 1.0, v32
	v_add_f32_e32 v33, 1.0, v33
	v_add_f32_e32 v34, 1.0, v34
	v_add_f32_e32 v35, 1.0, v35
	v_rcp_f32_e32 v32, v32
	v_rcp_f32_e32 v33, v33
	v_rcp_f32_e32 v34, v34
	v_rcp_f32_e32 v35, v35
	v_mul_f32_e32 v16, v16, v32
	v_mul_f32_e32 v17, v17, v33
	v_mul_f32_e32 v18, v18, v34
	v_mul_f32_e32 v19, v19, v35
	v_mul_f32_e32 v16, v20, v16
	v_mul_f32_e32 v17, v21, v17
	v_mul_f32_e32 v18, v22, v18
	v_mul_f32_e32 v19, v23, v19
	v_cvt_pk_bf16_f32 v16, v16, v17
	v_cvt_pk_bf16_f32 v17, v18, v19
	global_store_dwordx2 v48, v[16:17], s[94:95] sc1
	s_waitcnt vmcnt(9)
; __device__ __forceinline__ unsigned cvt_pk_bf16(float lo, float hi) { unsigned r; asm volatile("v_cvt_pk_bf16_f32 %0, %1, %2" : "=v"(r) : "v"(lo), "v"(hi)); return r; }
; __device__ __forceinline__ void xcd_barrier(const XcdBarrier& b) {
;     asm volatile("s_waitcnt vmcnt(0)" ::: "memory");
;     __syncthreads();
; __global__ void __launch_bounds__(NTHR, 2) hybrid_block_fwd(Args a) {
;     ...
;         for (int idx = gtid; idx < 256 * 2 * (FF / 4); idx += NT) {
;             const int f4 = (idx % (FF / 4)) * 4, rr = (idx / (FF / 4)) & 1, blk = idx / (2 * (FF / 4));
;             const bool seq0 = (blk & 127) == 0; const size_t row = (size_t)blk * 64 + rr;
;             const f32x4 z = (f32x4){0.f, 0.f, 0.f, 0.f};
;             const f32x4 gc = *(const f32x4*)(HEADG + ((size_t)blk * 2 + rr) * FF + f4), vv = *(const f32x4*)(HEADV + ((size_t)blk * 2 + rr) * FF + f4);
;             f32x4 p1, p2;
;             if (rr == 0) { p1 = seq0 ? z : *(const f32x4*)(TAILG + ((size_t)(blk - 1) * 2 + 1) * FF + f4); p2 = seq0 ? z : *(const f32x4*)(TAILG + ((size_t)(blk - 1) * 2 + 0) * FF + f4); }
;             else { p1 = *(const f32x4*)(HEADG + ((size_t)blk * 2 + 0) * FF + f4); p2 = seq0 ? z : *(const f32x4*)(TAILG + ((size_t)(blk - 1) * 2 + 1) * FF + f4); }
;             const f32x4 cv = *(const f32x4*)(ffn_conv_b + f4) + *(const f32x4*)(ffn_conv_w + f4) * p2 + *(const f32x4*)(ffn_conv_w + FF + f4) * p1 + *(const f32x4*)(ffn_conv_w + 2 * FF + f4) * gc;
;             u32x2 w; w.x = cvt_pk_bf16(gelu_tanh(cv[0]) * vv[0], gelu_tanh(cv[1]) * vv[1]); w.y = cvt_pk_bf16(gelu_tanh(cv[2]) * vv[2], gelu_tanh(cv[3]) * vv[3]);
;             *(u32x2*)(ACT + row * FF + f4) = w;
;         }
	v_lshrrev_b32_e32 v2, 1, v85
	v_and_b32_e32 v2, 0x7f, v2
	v_cmp_eq_u32_e32 vcc, 0, v2
	v_and_b32_e32 v3, 1, v85
	v_cmp_eq_u32_e64 s[8:9], 0, v3
	s_nop 1
	s_and_b64 s[8:9], s[8:9], vcc
	s_nop 1
	v_cndmask_b32_e64 v64, v64, 0, vcc
	v_cndmask_b32_e64 v60, v60, 0, s[8:9]
	v_cndmask_b32_e64 v65, v65, 0, vcc
	v_cndmask_b32_e64 v61, v61, 0, s[8:9]
	v_cndmask_b32_e64 v66, v66, 0, vcc
	v_cndmask_b32_e64 v62, v62, 0, s[8:9]
	v_cndmask_b32_e64 v67, v67, 0, vcc
	v_cndmask_b32_e64 v63, v63, 0, s[8:9]
	v_pk_fma_f32 v[66:67], v[66:67], v[74:75], v[70:71]
	v_pk_fma_f32 v[64:65], v[64:65], v[72:73], v[68:69]
	v_pk_fma_f32 v[62:63], v[62:63], v[78:79], v[66:67]
	v_pk_fma_f32 v[60:61], v[60:61], v[76:77], v[64:65]
	v_pk_fma_f32 v[54:55], v[54:55], v[82:83], v[62:63]
	v_pk_fma_f32 v[52:53], v[52:53], v[80:81], v[60:61]
	v_mul_f32_e32 v68, 0x3d922279, v52
	v_mul_f32_e32 v69, 0x3d922279, v53
	v_mul_f32_e32 v70, 0x3d922279, v54
	v_mul_f32_e32 v71, 0x3d922279, v55
	v_fmaak_f32 v68, v52, v68, 0x3fcc422a
	v_fmaak_f32 v69, v53, v69, 0x3fcc422a
	v_fmaak_f32 v70, v54, v70, 0x3fcc422a
	v_fmaak_f32 v71, v55, v71, 0x3fcc422a
	v_mul_f32_e32 v68, v52, v68
	v_mul_f32_e32 v69, v53, v69
	v_mul_f32_e32 v70, v54, v70
	v_mul_f32_e32 v71, v55, v71
	v_mul_f32_e32 v68, 0xbfb8aa3b, v68
	v_mul_f32_e32 v69, 0xbfb8aa3b, v69
	v_mul_f32_e32 v70, 0xbfb8aa3b, v70
	v_mul_f32_e32 v71, 0xbfb8aa3b, v71
	v_exp_f32_e32 v68, v68
	v_exp_f32_e32 v69, v69
	v_exp_f32_e32 v70, v70
	v_exp_f32_e32 v71, v71
	v_add_f32_e32 v68, 1.0, v68
	v_add_f32_e32 v69, 1.0, v69
	v_add_f32_e32 v70, 1.0, v70
	v_add_f32_e32 v71, 1.0, v71
	v_rcp_f32_e32 v68, v68
	v_rcp_f32_e32 v69, v69
	v_rcp_f32_e32 v70, v70
	v_rcp_f32_e32 v71, v71
	v_mul_f32_e32 v52, v52, v68
	v_mul_f32_e32 v53, v53, v69
	v_mul_f32_e32 v54, v54, v70
	v_mul_f32_e32 v55, v55, v71
	v_mul_f32_e32 v52, v56, v52
	v_mul_f32_e32 v53, v57, v53
	v_mul_f32_e32 v54, v58, v54
	v_mul_f32_e32 v55, v59, v55
	v_cvt_pk_bf16_f32 v52, v52, v53
	v_cvt_pk_bf16_f32 v53, v54, v55
	global_store_dwordx2 v84, v[52:53], s[94:95] sc1
	s_waitcnt vmcnt(2)
	v_lshrrev_b32_e32 v2, 1, v121
	v_and_b32_e32 v2, 0x7f, v2
	v_cmp_eq_u32_e32 vcc, 0, v2
	v_and_b32_e32 v3, 1, v121
	v_cmp_eq_u32_e64 s[8:9], 0, v3
	s_nop 1
	s_and_b64 s[8:9], s[8:9], vcc
	s_nop 1
	v_cndmask_b32_e64 v100, v100, 0, vcc
	v_cndmask_b32_e64 v96, v96, 0, s[8:9]
	v_cndmask_b32_e64 v101, v101, 0, vcc
	v_cndmask_b32_e64 v97, v97, 0, s[8:9]
	v_cndmask_b32_e64 v102, v102, 0, vcc
	v_cndmask_b32_e64 v98, v98, 0, s[8:9]
	v_cndmask_b32_e64 v103, v103, 0, vcc
	v_cndmask_b32_e64 v99, v99, 0, s[8:9]
	v_pk_fma_f32 v[102:103], v[102:103], v[110:111], v[106:107]
	v_pk_fma_f32 v[100:101], v[100:101], v[108:109], v[104:105]
	v_pk_fma_f32 v[98:99], v[98:99], v[114:115], v[102:103]
	v_pk_fma_f32 v[96:97], v[96:97], v[112:113], v[100:101]
	v_pk_fma_f32 v[90:91], v[90:91], v[118:119], v[98:99]
	v_pk_fma_f32 v[88:89], v[88:89], v[116:117], v[96:97]
	v_mul_f32_e32 v104, 0x3d922279, v88
	v_mul_f32_e32 v105, 0x3d922279, v89
	v_mul_f32_e32 v106, 0x3d922279, v90
	v_mul_f32_e32 v107, 0x3d922279, v91
	v_fmaak_f32 v104, v88, v104, 0x3fcc422a
	v_fmaak_f32 v105, v89, v105, 0x3fcc422a
	v_fmaak_f32 v106, v90, v106, 0x3fcc422a
	v_fmaak_f32 v107, v91, v107, 0x3fcc422a
	v_mul_f32_e32 v104, v88, v104
	v_mul_f32_e32 v105, v89, v105
	v_mul_f32_e32 v106, v90, v106
	v_mul_f32_e32 v107, v91, v107
	v_mul_f32_e32 v104, 0xbfb8aa3b, v104
	v_mul_f32_e32 v105, 0xbfb8aa3b, v105
	v_mul_f32_e32 v106, 0xbfb8aa3b, v106
	v_mul_f32_e32 v107, 0xbfb8aa3b, v107
	v_exp_f32_e32 v104, v104
	v_exp_f32_e32 v105, v105
	v_exp_f32_e32 v106, v106
	v_exp_f32_e32 v107, v107
	v_add_f32_e32 v104, 1.0, v104
	v_add_f32_e32 v105, 1.0, v105
	v_add_f32_e32 v106, 1.0, v106
	v_add_f32_e32 v107, 1.0, v107
	v_rcp_f32_e32 v104, v104
	v_rcp_f32_e32 v105, v105
	v_rcp_f32_e32 v106, v106
	v_rcp_f32_e32 v107, v107
	v_mul_f32_e32 v88, v88, v104
	v_mul_f32_e32 v89, v89, v105
	v_mul_f32_e32 v90, v90, v106
	v_mul_f32_e32 v91, v91, v107
	v_mul_f32_e32 v88, v92, v88
	v_mul_f32_e32 v89, v93, v89
	v_mul_f32_e32 v90, v94, v90
	v_mul_f32_e32 v91, v95, v91
	v_cvt_pk_bf16_f32 v88, v88, v89
	v_cvt_pk_bf16_f32 v89, v90, v91
	global_store_dwordx2 v120, v[88:89], s[94:95] sc1
	s_or_b64 exec, exec, s[4:5]
	s_waitcnt vmcnt(0)
	s_barrier
	v_readfirstlane_b32 s0, v212
	s_cmp_lg_u32 s0, 64
	s_cbranch_scc1 .Linv_8
	s_sleep 48
	buffer_inv sc1
	s_waitcnt vmcnt(0)
